# adds: neighbourhood-attention bias chain de-serialised (16 exec-masked LDS round trips per step -> one batch of unconditional reads + v_cndmask)
# baseline (speedup 1.0000x reference)
; #define LAS __attribute__((address_space(3)))
; DI void walk_na(int Ssh, int nseq, int layer, const bf16_t* PROJ, bf16_t* O, const float* rpb, LAS unsigned char* lds, LAS float* bias, int wid, int lane, int wgi) {
;     ...
;         const int r = c_r0 + (w4 >> 1); const int rs = min(max(r - 4, 0), R - 8); const int kr = min(max(c_r0 - 4, 0), R - 8) + s;
;         if (kr >= rs && kr < rs + 8) {
;             f32x16 p0, p1;
;             qk64<4, 0>(p0, p1, cur, qr, r32, hi);
;             const int dr = kr - r + 7;
;             LAS const float* bp = bias + dr * 31 + (15 - c + 4 * hi);
;             const unsigned ub = (unsigned)(4 * hi - cs);
; #pragma unroll
;             for (int rr = 0; rr < 16; ++rr) {
;                 const int c0 = (rr & 3) + 8 * (rr >> 2);
;                 const float b0 = bp[c0], b1 = bp[c0 + 32];
;                 p0[rr] = (ub + (unsigned)c0 < 16u) ? p0[rr] + b0 : -INFINITY;
;                 p1[rr] = (ub + (unsigned)c0 + 32u < 16u) ? p1[rr] + b1 : -INFINITY;
;             }
;             softmax_pv(p0, p1, m, l, o0, o1, cur + 8192, lane, hi);
.LBB0_355:
	v_readlane_b32 s1, v252, 37
	s_add_i32 s36, s23, s1
	s_max_i32 s1, s36, 4
	s_add_i32 s1, s1, -4
	v_readlane_b32 s16, v254, 17
	s_min_i32 s18, s1, s16
	s_max_i32 s1, s23, 4
	s_add_i32 s1, s1, -4
	s_min_i32 s1, s1, s16
	s_add_i32 s1, s1, s0
	s_cmp_ge_i32 s1, s18
	s_cselect_b64 s[16:17], -1, 0
	s_add_i32 s18, s18, 8
	s_cmp_lt_i32 s1, s18
	s_cselect_b64 s[18:19], -1, 0
	s_and_b64 s[16:17], s[16:17], s[18:19]
	s_andn2_b64 vcc, exec, s[16:17]
	s_cbranch_vccnz .LBB0_389
	s_waitcnt vmcnt(3)
	ds_read_b128 v[2:5], v185
	s_waitcnt vmcnt(2)
	ds_read_b128 v[6:9], v185 offset:512
	s_waitcnt vmcnt(1)
	ds_read_b128 v[10:13], v186
	ds_read_b128 v[196:199], v186 offset:512
	ds_read_b128 v[200:203], v187
	ds_read_b128 v[204:207], v187 offset:512
	ds_read_b128 v[208:211], v188
	ds_read_b128 v[212:215], v188 offset:512
	s_waitcnt lgkmcnt(7)
	v_mfma_f32_32x32x16_bf16 v[64:79], v[2:5], v[124:127], 0
	s_sub_i32 s1, s1, s36
	s_mulk_i32 s1, 0x7c
	v_add_u32_e32 v4, s1, v182
	ds_read_b32 v2, v4 offset:1056
	v_mov_b32_e32 v0, 0xff800000
	v_mov_b32_e32 v14, 0xff800000
	s_waitcnt vmcnt(0) lgkmcnt(7)
	v_mfma_f32_32x32x16_bf16 v[48:63], v[6:9], v[124:127], 0
	s_waitcnt lgkmcnt(6)
	v_mfma_f32_32x32x16_bf16 v[64:79], v[10:13], v[120:123], v[64:79]
	s_waitcnt lgkmcnt(5)
	v_mfma_f32_32x32x16_bf16 v[48:63], v[196:199], v[120:123], v[48:63]
	s_waitcnt lgkmcnt(4)
	v_mfma_f32_32x32x16_bf16 v[64:79], v[200:203], v[116:119], v[64:79]
	s_waitcnt lgkmcnt(3)
	v_mfma_f32_32x32x16_bf16 v[48:63], v[204:207], v[116:119], v[48:63]
	s_waitcnt lgkmcnt(2)
	v_mfma_f32_32x32x16_bf16 v[64:79], v[208:211], v[112:115], v[64:79]
	s_waitcnt lgkmcnt(1)
	v_mfma_f32_32x32x16_bf16 v[48:63], v[212:215], v[112:115], v[48:63]
	ds_read_b32 v219, v4 offset:928
	ds_read_b32 v220, v4 offset:932
	ds_read_b32 v221, v4 offset:936
	ds_read_b32 v222, v4 offset:940
	ds_read_b32 v223, v4 offset:960
	ds_read_b32 v224, v4 offset:964
	ds_read_b32 v225, v4 offset:968
	ds_read_b32 v226, v4 offset:972
	ds_read_b32 v227, v4 offset:992
	ds_read_b32 v228, v4 offset:996
	ds_read_b32 v229, v4 offset:1000
	ds_read_b32 v230, v4 offset:1004
	ds_read_b32 v231, v4 offset:1024
	ds_read_b32 v238, v4 offset:1028
	ds_read_b32 v239, v4 offset:1032
	ds_read_b32 v240, v4 offset:1036
	v_readlane_b32 s16, v255, 16
	v_readlane_b32 s17, v255, 17
	s_and_b64 s[16:17], exec, s[16:17]
	s_waitcnt lgkmcnt(0)
	v_add_f32_e32 v219, v64, v219
	v_cndmask_b32_e64 v14, v245, v219, s[16:17]
	ds_read_b32 v3, v4 offset:1060
	v_add_f32_e32 v220, v65, v220
	v_cndmask_b32_e64 v0, v245, v220, s[42:43]
	ds_read_b32 v5, v4 offset:1064
	v_add_f32_e32 v221, v66, v221
	v_cndmask_b32_e64 v167, v245, v221, s[50:51]
	ds_read_b32 v6, v4 offset:1068
	v_add_f32_e32 v222, v67, v222
	v_cndmask_b32_e64 v166, v245, v222, s[54:55]
	ds_read_b32 v7, v4 offset:1088
	v_add_f32_e32 v223, v68, v223
	v_cndmask_b32_e64 v195, v245, v223, s[58:59]
	ds_read_b32 v8, v4 offset:1092
	v_add_f32_e32 v224, v69, v224
	v_cndmask_b32_e64 v169, v245, v224, s[62:63]
	ds_read_b32 v9, v4 offset:1096
	v_add_f32_e32 v225, v70, v225
	v_cndmask_b32_e64 v197, v245, v225, s[66:67]
	ds_read_b32 v10, v4 offset:1100
	v_add_f32_e32 v226, v71, v226
	v_cndmask_b32_e64 v196, v245, v226, s[70:71]
	ds_read_b32 v11, v4 offset:1120
	v_add_f32_e32 v227, v72, v227
	v_cndmask_b32_e64 v199, v245, v227, s[74:75]
	ds_read_b32 v12, v4 offset:1124
	v_add_f32_e32 v228, v73, v228
	v_cndmask_b32_e64 v198, v245, v228, s[78:79]
	ds_read_b32 v13, v4 offset:1128
	v_add_f32_e32 v229, v74, v229
	v_cndmask_b32_e64 v201, v245, v229, s[82:83]
	ds_read_b32 v15, v4 offset:1132
	v_add_f32_e32 v230, v75, v230
	v_cndmask_b32_e64 v200, v245, v230, s[86:87]
	ds_read_b32 v64, v4 offset:1152
	v_add_f32_e32 v231, v76, v231
	v_cndmask_b32_e64 v75, v245, v231, s[90:91]
	ds_read_b32 v65, v4 offset:1156
	v_add_f32_e32 v238, v77, v238
	v_cndmask_b32_e64 v73, v245, v238, s[94:95]
	ds_read_b32 v67, v4 offset:1160
	v_add_f32_e32 v239, v78, v239
	v_cndmask_b32_e64 v74, v245, v239, s[4:5]
	ds_read_b32 v66, v4 offset:1164
	v_add_f32_e32 v240, v79, v240
	v_cndmask_b32_e64 v72, v245, v240, s[8:9]
	s_waitcnt lgkmcnt(1)
	v_add_f32_e32 v4, v62, v67
	v_cndmask_b32_e64 v205, v245, v4, s[6:7]
	v_add_f32_e32 v4, v61, v65
	v_cndmask_b32_e64 v207, v245, v4, s[96:97]
	v_add_f32_e32 v4, v60, v64
	v_cndmask_b32_e64 v208, v245, v4, s[92:93]
	v_add_f32_e32 v4, v59, v15
	v_cndmask_b32_e64 v209, v245, v4, s[88:89]
	v_add_f32_e32 v4, v58, v13
	v_cndmask_b32_e64 v204, v245, v4, s[84:85]
	v_add_f32_e32 v4, v57, v12
	v_cndmask_b32_e64 v206, v245, v4, s[80:81]
	v_add_f32_e32 v4, v56, v11
	v_cndmask_b32_e64 v210, v245, v4, s[76:77]
	v_add_f32_e32 v4, v55, v10
	v_cndmask_b32_e64 v211, v245, v4, s[72:73]
	v_add_f32_e32 v4, v54, v9
	v_cndmask_b32_e64 v212, v245, v4, s[68:69]
	v_add_f32_e32 v4, v53, v8
	v_cndmask_b32_e64 v70, v245, v4, s[64:65]
	v_add_f32_e32 v4, v52, v7
	v_cndmask_b32_e64 v71, v245, v4, s[60:61]
	v_add_f32_e32 v4, v51, v6
	v_cndmask_b32_e64 v68, v245, v4, s[56:57]
	v_add_f32_e32 v4, v50, v5
	v_add_f32_e32 v2, v48, v2
	v_cndmask_b32_e64 v69, v245, v4, s[52:53]
	v_add_f32_e32 v3, v49, v3
	v_cndmask_b32_e64 v76, v245, v2, s[20:21]
	s_waitcnt lgkmcnt(0)
; DI unsigned cvtpk(float lo, float hi) { f32x2 v = {lo, hi}; bf16x2_t b = __builtin_convertvector(v, bf16x2_t); return __builtin_bit_cast(unsigned, b); }
; DI float fexp2(float x) { return __builtin_amdgcn_exp2f(x); }
; DI float max2f(float a, float b) { float r; asm("v_max_f32_e32 %0, %1, %2" : "=v"(r) : "v"(a), "v"(b)); return r; }
; DI float xhalf_max(float v) { auto rr = __builtin_amdgcn_permlane32_swap(__float_as_uint(v), __float_as_uint(v), false, false); return max2f(__uint_as_float(rr[0]), __uint_as_float(rr[1])); }
; DI void softmax_pv(f32x16& p0, f32x16& p1, float& m, float& l, f32x16& o0, f32x16& o1, LAS const unsigned char* vslot, int lane, int hi) {
;     ...
;     for (int ks = 0; ks < 4; ++ks) { vlo0[ks] = vtr(vp + ks * 1024); vhi0[ks] = vtr(vp + ks * 1024 + 512); vlo1[ks] = vtr(vp + 4096 + ks * 1024); vhi1[ks] = vtr(vp + 4096 + ks * 1024 + 512); }
;     __builtin_amdgcn_sched_barrier(0);
;     const float mx = xhalf_max(rowmax32(p0, p1));
;     const float mn = max2f(m, mx); const float f = fexp2(m - mn); m = mn;
;     float s = 0.f;
; #pragma unroll
;     for (int r = 0; r < 16; ++r) { p0[r] = fexp2(p0[r] - mn); p1[r] = fexp2(p1[r] - mn); s += p0[r] + p1[r]; }
;     s = xhalf_sum(s);
;     l = l * f + s;
; #pragma unroll
;     for (int r = 0; r < 16; ++r) { o0[r] *= f; o1[r] *= f; }
;     u32x4 pw[4];
;     pw[0] = (u32x4){cvtpk(p0[0], p0[1]), cvtpk(p0[2], p0[3]), cvtpk(p0[4], p0[5]), cvtpk(p0[6], p0[7])};
;     pw[1] = (u32x4){cvtpk(p0[8], p0[9]), cvtpk(p0[10], p0[11]), cvtpk(p0[12], p0[13]), cvtpk(p0[14], p0[15])};
;     pw[2] = (u32x4){cvtpk(p1[0], p1[1]), cvtpk(p1[2], p1[3]), cvtpk(p1[4], p1[5]), cvtpk(p1[6], p1[7])};
;     pw[3] = (u32x4){cvtpk(p1[8], p1[9]), cvtpk(p1[10], p1[11]), cvtpk(p1[12], p1[13]), cvtpk(p1[14], p1[15])};
; #pragma unroll
;     for (int ks = 0; ks < 4; ++ks) {
;         const bf16x8 v0 = (bf16x8){vlo0[ks][0], vlo0[ks][1], vlo0[ks][2], vlo0[ks][3], vhi0[ks][0], vhi0[ks][1], vhi0[ks][2], vhi0[ks][3]};
;         const bf16x8 v1 = (bf16x8){vlo1[ks][0], vlo1[ks][1], vlo1[ks][2], vlo1[ks][3], vhi1[ks][0], vhi1[ks][1], vhi1[ks][2], vhi1[ks][3]};
;         const bf16x8 pf = __builtin_bit_cast(bf16x8, pw[ks]);
;         o0 = __builtin_amdgcn_mfma_f32_32x32x16_bf16(v0, pf, o0, 0, 0, 0);
;         o1 = __builtin_amdgcn_mfma_f32_32x32x16_bf16(v1, pf, o1, 0, 0, 0);
;     }
	v_add_f32_e32 v2, v63, v66
	v_add_u32_e32 v4, v178, v177
	v_cndmask_b32_e64 v15, v245, v3, s[48:49]
	v_cndmask_b32_e64 v213, v245, v2, s[10:11]
	ds_read_b64_tr_b16 v[64:65], v4 offset:8192
	ds_read_b64_tr_b16 v[66:67], v4 offset:8704
	ds_read_b64_tr_b16 v[60:61], v4 offset:12288
	ds_read_b64_tr_b16 v[62:63], v4 offset:12800
	ds_read_b64_tr_b16 v[52:53], v4 offset:9216
	ds_read_b64_tr_b16 v[54:55], v4 offset:9728
	ds_read_b64_tr_b16 v[56:57], v4 offset:13312
	ds_read_b64_tr_b16 v[58:59], v4 offset:13824
	ds_read_b64_tr_b16 v[48:49], v4 offset:10240
	ds_read_b64_tr_b16 v[50:51], v4 offset:10752
	ds_read_b64_tr_b16 v[10:11], v4 offset:14336
	ds_read_b64_tr_b16 v[12:13], v4 offset:14848
	ds_read_b64_tr_b16 v[6:7], v4 offset:11264
	ds_read_b64_tr_b16 v[8:9], v4 offset:11776
	ds_read_b64_tr_b16 v[2:3], v4 offset:15360
	ds_read_b64_tr_b16 v[4:5], v4 offset:15872
	v_max3_f32 v77, v14, v0, v76
	v_max3_f32 v78, v167, v166, v15
	s_nop 0
	v_max3_f32 v77, v77, v69, v68
	v_max3_f32 v78, v78, v197, v196
	s_nop 0
	v_max3_f32 v77, v77, v195, v169
	v_max3_f32 v78, v78, v212, v211
	s_nop 0
	v_max3_f32 v77, v77, v71, v70
	v_max3_f32 v78, v78, v201, v200
	s_nop 0
	v_max3_f32 v77, v77, v199, v198
	v_max3_f32 v78, v78, v204, v209
	s_nop 0
	v_max3_f32 v77, v77, v210, v206
	v_max3_f32 v78, v78, v74, v72
	s_nop 0
	v_max3_f32 v77, v77, v75, v73
	v_max3_f32 v78, v78, v205, v213
	s_nop 0
	v_max3_f32 v77, v77, v208, v207
	s_nop 0
	v_max_f32_e32 v77, v77, v78
	s_nop 0
	v_mov_b32_e32 v78, v77
	s_nop 1
	v_permlane32_swap_b32_e32 v77, v78
	v_max_f32_e32 v77, v77, v78
	s_nop 0
	v_max_f32_e32 v214, v194, v77
	s_nop 0
	v_sub_f32_e32 v14, v14, v214
	v_exp_f32_e32 v215, v14
	v_sub_f32_e32 v14, v76, v214
	v_sub_f32_e32 v0, v0, v214
	v_exp_f32_e32 v216, v14
	v_exp_f32_e32 v76, v0
	v_sub_f32_e32 v0, v15, v214
	v_exp_f32_e32 v0, v0
	v_add_f32_e32 v77, v215, v216
	v_sub_f32_e32 v75, v75, v214
	v_sub_f32_e32 v73, v73, v214
	v_pk_add_f32 v[14:15], v[76:77], v[0:1]
	s_nop 0
	v_pk_add_f32 v[14:15], v[14:15], v[14:15] op_sel_hi:[0,1]
	v_sub_f32_e32 v14, v167, v214
	v_exp_f32_e32 v77, v14
	v_sub_f32_e32 v14, v69, v214
	v_exp_f32_e32 v217, v14
	v_sub_f32_e32 v14, v166, v214
	v_exp_f32_e32 v78, v14
	v_sub_f32_e32 v14, v68, v214
	v_exp_f32_e32 v14, v14
	v_add_f32_e32 v79, v77, v217
	v_pk_add_f32 v[68:69], v[78:79], v[14:15]
	s_nop 0
	v_pk_add_f32 v[68:69], v[68:69], v[68:69] op_sel_hi:[0,1]
	v_sub_f32_e32 v68, v71, v214
	v_sub_f32_e32 v15, v195, v214
	v_exp_f32_e32 v79, v68
	v_sub_f32_e32 v68, v169, v214
	v_exp_f32_e32 v15, v15
	v_exp_f32_e32 v166, v68
	v_sub_f32_e32 v68, v70, v214
	v_exp_f32_e32 v68, v68
	v_add_f32_e32 v167, v15, v79
	v_pk_add_f32 v[70:71], v[166:167], v[68:69]
	s_nop 0
	v_pk_add_f32 v[202:203], v[70:71], v[70:71] op_sel_hi:[0,1]
	v_sub_f32_e32 v70, v212, v214
	v_sub_f32_e32 v69, v197, v214
	v_exp_f32_e32 v167, v70
	v_sub_f32_e32 v70, v196, v214
	v_exp_f32_e32 v69, v69
	v_exp_f32_e32 v196, v70
	v_sub_f32_e32 v70, v211, v214
	v_exp_f32_e32 v202, v70
	v_add_f32_e32 v197, v69, v167
	v_pk_add_f32 v[70:71], v[196:197], v[202:203]
	s_nop 0
	v_pk_add_f32 v[70:71], v[70:71], v[70:71] op_sel_hi:[0,1]
	v_sub_f32_e32 v70, v199, v214
	v_exp_f32_e32 v169, v70
	v_sub_f32_e32 v70, v210, v214
	v_exp_f32_e32 v197, v70
	v_sub_f32_e32 v70, v198, v214
	v_exp_f32_e32 v198, v70
	v_sub_f32_e32 v70, v206, v214
	v_exp_f32_e32 v70, v70
	v_add_f32_e32 v199, v169, v197
	v_sub_f32_e32 v203, v194, v214
	v_exp_f32_e32 v206, v73
	v_pk_add_f32 v[194:195], v[198:199], v[70:71]
	v_sub_f32_e32 v199, v200, v214
	v_pk_add_f32 v[194:195], v[194:195], v[194:195] op_sel_hi:[0,1]
	v_sub_f32_e32 v194, v204, v214
	v_exp_f32_e32 v204, v203
	v_exp_f32_e32 v200, v199
	v_exp_f32_e32 v199, v75
	v_sub_f32_e32 v73, v74, v214
	v_pk_mul_f32 v[30:31], v[30:31], v[204:205] op_sel_hi:[1,0]
	v_pk_mul_f32 v[28:29], v[28:29], v[204:205] op_sel_hi:[1,0]
	v_pk_mul_f32 v[26:27], v[26:27], v[204:205] op_sel_hi:[1,0]
	v_pk_mul_f32 v[24:25], v[24:25], v[204:205] op_sel_hi:[1,0]
	v_pk_mul_f32 v[22:23], v[22:23], v[204:205] op_sel_hi:[1,0]
	v_pk_mul_f32 v[20:21], v[20:21], v[204:205] op_sel_hi:[1,0]
	v_pk_mul_f32 v[18:19], v[18:19], v[204:205] op_sel_hi:[1,0]
	v_pk_mul_f32 v[16:17], v[16:17], v[204:205] op_sel_hi:[1,0]
	v_pk_mul_f32 v[46:47], v[46:47], v[204:205] op_sel_hi:[1,0]
	v_cvt_pk_bf16_f32 v74, v215, v76
	v_cvt_pk_bf16_f32 v75, v77, v78
	v_cvt_pk_bf16_f32 v76, v15, v166
	v_cvt_pk_bf16_f32 v77, v69, v196
	v_pk_mul_f32 v[44:45], v[44:45], v[204:205] op_sel_hi:[1,0]
	v_pk_mul_f32 v[42:43], v[42:43], v[204:205] op_sel_hi:[1,0]
	v_pk_mul_f32 v[40:41], v[40:41], v[204:205] op_sel_hi:[1,0]
	v_pk_mul_f32 v[38:39], v[38:39], v[204:205] op_sel_hi:[1,0]
	v_pk_mul_f32 v[36:37], v[36:37], v[204:205] op_sel_hi:[1,0]
	v_pk_mul_f32 v[34:35], v[34:35], v[204:205] op_sel_hi:[1,0]
	v_pk_mul_f32 v[32:33], v[32:33], v[204:205] op_sel_hi:[1,0]
	s_waitcnt lgkmcnt(14)
	v_mfma_f32_32x32x16_bf16 v[16:31], v[64:67], v[74:77], v[16:31]
	v_sub_f32_e32 v71, v201, v214
	v_sub_f32_e32 v15, v72, v214
	v_exp_f32_e32 v71, v71
	v_exp_f32_e32 v65, v73
	v_exp_f32_e32 v64, v15
	v_exp_f32_e32 v66, v194
	v_sub_f32_e32 v15, v209, v214
	s_waitcnt lgkmcnt(12)
	v_mfma_f32_32x32x16_bf16 v[32:47], v[60:63], v[74:77], v[32:47]
	v_cvt_pk_bf16_f32 v60, v169, v198
	v_cvt_pk_bf16_f32 v61, v71, v200
	v_cvt_pk_bf16_f32 v62, v199, v206
	v_cvt_pk_bf16_f32 v63, v65, v64
	v_exp_f32_e32 v194, v15
	v_add_f32_e32 v201, v71, v66
	v_sub_f32_e32 v15, v208, v214
	s_waitcnt lgkmcnt(10)
	v_mfma_f32_32x32x16_bf16 v[16:31], v[52:55], v[60:63], v[16:31]
	v_add_f32_e64 v52, v200, v194
	v_add_f32_e64 v53, v201, v195
	v_cvt_pk_bf16_f32 v54, v79, v68
	v_cvt_pk_bf16_f32 v55, v167, v202
	s_waitcnt lgkmcnt(8)
	v_mfma_f32_32x32x16_bf16 v[32:47], v[56:59], v[60:63], v[32:47]
	v_add_f32_e64 v56, v52, v52
	v_add_f32_e64 v57, v52, v53
	v_exp_f32_e32 v58, v15
	v_cvt_pk_bf16_f32 v52, v216, v0
	v_sub_f32_e32 v0, v207, v214
	v_exp_f32_e32 v56, v0
	v_cvt_pk_bf16_f32 v53, v217, v14
	v_add_f32_e32 v207, v199, v58
	v_sub_f32_e32 v0, v205, v214
	s_waitcnt lgkmcnt(6)
	v_mfma_f32_32x32x16_bf16 v[16:31], v[48:51], v[52:55], v[16:31]
	v_add_f32_e64 v14, v206, v56
	v_add_f32_e64 v15, v207, v57
	v_exp_f32_e32 v0, v0
	v_pk_add_f32 v[14:15], v[14:15], v[14:15] op_sel_hi:[0,1]
	v_add_f32_e32 v65, v65, v0
	s_waitcnt lgkmcnt(4)
	v_mfma_f32_32x32x16_bf16 v[32:47], v[10:13], v[52:55], v[32:47]
	v_sub_f32_e32 v10, v213, v214
	v_exp_f32_e32 v14, v10
	v_cvt_pk_bf16_f32 v10, v197, v70
	v_cvt_pk_bf16_f32 v11, v66, v194
	v_cvt_pk_bf16_f32 v12, v58, v56
	v_cvt_pk_bf16_f32 v13, v0, v14
	v_mov_b32_e32 v194, v214
	s_waitcnt lgkmcnt(2)
	v_mfma_f32_32x32x16_bf16 v[16:31], v[6:9], v[10:13], v[16:31]
	v_add_f32_e64 v6, v64, v14
	v_add_f32_e64 v7, v65, v15
	v_pk_add_f32 v[6:7], v[6:7], v[6:7] op_sel:[0,1] op_sel_hi:[1,0]
	s_nop 0
	v_mov_b32_e32 v0, v6
	s_nop 1
	v_permlane32_swap_b32_e32 v6, v0
	s_waitcnt lgkmcnt(0)
	v_mfma_f32_32x32x16_bf16 v[32:47], v[2:5], v[10:13], v[32:47]
	v_add_f32_e32 v0, v6, v0
	v_fmac_f32_e32 v0, v193, v204
	v_mov_b32_e32 v193, v0

; #define LAS __attribute__((address_space(3)))
; DI void walk_na(int Ssh, int nseq, int layer, const bf16_t* PROJ, bf16_t* O, const float* rpb, LAS unsigned char* lds, LAS float* bias, int wid, int lane, int wgi) {
;     ...
;         const int r = c_r0 + (w4 >> 1); const int rs = min(max(r - 4, 0), R - 8); const int kr = min(max(c_r0 - 4, 0), R - 8) + s;
;         if (kr >= rs && kr < rs + 8) {
;             f32x16 p0, p1;
;             qk64<4, 0>(p0, p1, cur, qr, r32, hi);
;             const int dr = kr - r + 7;
;             LAS const float* bp = bias + dr * 31 + (15 - c + 4 * hi);
;             const unsigned ub = (unsigned)(4 * hi - cs);
; #pragma unroll
;             for (int rr = 0; rr < 16; ++rr) {
;                 const int c0 = (rr & 3) + 8 * (rr >> 2);
;                 const float b0 = bp[c0], b1 = bp[c0 + 32];
;                 p0[rr] = (ub + (unsigned)c0 < 16u) ? p0[rr] + b0 : -INFINITY;
;                 p1[rr] = (ub + (unsigned)c0 + 32u < 16u) ? p1[rr] + b1 : -INFINITY;
;             }
;             softmax_pv(p0, p1, m, l, o0, o1, cur + 8192, lane, hi);
.LBB0_417:
	s_waitcnt vmcnt(3)
	ds_read_b128 v[2:5], v185 offset:16384
	s_waitcnt vmcnt(2)
	ds_read_b128 v[6:9], v185 offset:16896
	s_waitcnt vmcnt(1)
	ds_read_b128 v[10:13], v186 offset:16384
	ds_read_b128 v[196:199], v186 offset:16896
	ds_read_b128 v[200:203], v187 offset:16384
	ds_read_b128 v[204:207], v187 offset:16896
	ds_read_b128 v[208:211], v188 offset:16384
	ds_read_b128 v[212:215], v188 offset:16896
	s_waitcnt lgkmcnt(7)
	v_mfma_f32_32x32x16_bf16 v[64:79], v[2:5], v[124:127], 0
	s_sub_i32 s1, s1, s36
	s_mulk_i32 s1, 0x7c
	v_add_u32_e32 v4, s1, v182
	ds_read_b32 v2, v4 offset:1056
	v_mov_b32_e32 v0, 0xff800000
	v_mov_b32_e32 v14, 0xff800000
	s_waitcnt vmcnt(0) lgkmcnt(7)
	v_mfma_f32_32x32x16_bf16 v[48:63], v[6:9], v[124:127], 0
	s_waitcnt lgkmcnt(6)
	v_mfma_f32_32x32x16_bf16 v[64:79], v[10:13], v[120:123], v[64:79]
	s_waitcnt lgkmcnt(5)
	v_mfma_f32_32x32x16_bf16 v[48:63], v[196:199], v[120:123], v[48:63]
	s_waitcnt lgkmcnt(4)
	v_mfma_f32_32x32x16_bf16 v[64:79], v[200:203], v[116:119], v[64:79]
	s_waitcnt lgkmcnt(3)
	v_mfma_f32_32x32x16_bf16 v[48:63], v[204:207], v[116:119], v[48:63]
	s_waitcnt lgkmcnt(2)
	v_mfma_f32_32x32x16_bf16 v[64:79], v[208:211], v[112:115], v[64:79]
	s_waitcnt lgkmcnt(1)
	v_mfma_f32_32x32x16_bf16 v[48:63], v[212:215], v[112:115], v[48:63]
	ds_read_b32 v219, v4 offset:928
	ds_read_b32 v220, v4 offset:932
	ds_read_b32 v221, v4 offset:936
	ds_read_b32 v222, v4 offset:940
	ds_read_b32 v223, v4 offset:960
	ds_read_b32 v224, v4 offset:964
	ds_read_b32 v225, v4 offset:968
	ds_read_b32 v226, v4 offset:972
	ds_read_b32 v227, v4 offset:992
	ds_read_b32 v228, v4 offset:996
	ds_read_b32 v229, v4 offset:1000
	ds_read_b32 v230, v4 offset:1004
	ds_read_b32 v231, v4 offset:1024
	ds_read_b32 v238, v4 offset:1028
	ds_read_b32 v239, v4 offset:1032
	ds_read_b32 v240, v4 offset:1036
	v_readlane_b32 s16, v255, 16
	v_readlane_b32 s17, v255, 17
	s_and_b64 s[16:17], exec, s[16:17]
	s_waitcnt lgkmcnt(0)
	v_add_f32_e32 v219, v64, v219
	v_cndmask_b32_e64 v14, v245, v219, s[16:17]
	ds_read_b32 v3, v4 offset:1060
	v_add_f32_e32 v220, v65, v220
	v_cndmask_b32_e64 v0, v245, v220, s[42:43]
	ds_read_b32 v5, v4 offset:1064
	v_add_f32_e32 v221, v66, v221
	v_cndmask_b32_e64 v168, v245, v221, s[50:51]
	ds_read_b32 v6, v4 offset:1068
	v_add_f32_e32 v222, v67, v222
	v_cndmask_b32_e64 v167, v245, v222, s[54:55]
	ds_read_b32 v7, v4 offset:1088
	v_add_f32_e32 v223, v68, v223
	v_cndmask_b32_e64 v196, v245, v223, s[58:59]
	ds_read_b32 v8, v4 offset:1092
	v_add_f32_e32 v224, v69, v224
	v_cndmask_b32_e64 v169, v245, v224, s[62:63]
	ds_read_b32 v9, v4 offset:1096
	v_add_f32_e32 v225, v70, v225
	v_cndmask_b32_e64 v198, v245, v225, s[66:67]
	ds_read_b32 v10, v4 offset:1100
	v_add_f32_e32 v226, v71, v226
	v_cndmask_b32_e64 v197, v245, v226, s[70:71]
	ds_read_b32 v11, v4 offset:1120
	v_add_f32_e32 v227, v72, v227
	v_cndmask_b32_e64 v200, v245, v227, s[74:75]
	ds_read_b32 v12, v4 offset:1124
	v_add_f32_e32 v228, v73, v228
	v_cndmask_b32_e64 v199, v245, v228, s[78:79]
	ds_read_b32 v13, v4 offset:1128
	v_add_f32_e32 v229, v74, v229
	v_cndmask_b32_e64 v202, v245, v229, s[82:83]
	ds_read_b32 v15, v4 offset:1132
	v_add_f32_e32 v230, v75, v230
	v_cndmask_b32_e64 v201, v245, v230, s[86:87]
	ds_read_b32 v64, v4 offset:1152
	v_add_f32_e32 v231, v76, v231
	v_cndmask_b32_e64 v75, v245, v231, s[90:91]
	ds_read_b32 v65, v4 offset:1156
	v_add_f32_e32 v238, v77, v238
	v_cndmask_b32_e64 v73, v245, v238, s[94:95]
	ds_read_b32 v67, v4 offset:1160
	v_add_f32_e32 v239, v78, v239
	v_cndmask_b32_e64 v74, v245, v239, s[4:5]
	ds_read_b32 v66, v4 offset:1164
	v_add_f32_e32 v240, v79, v240
	v_cndmask_b32_e64 v72, v245, v240, s[8:9]
	s_waitcnt lgkmcnt(1)
	v_add_f32_e32 v4, v62, v67
	v_cndmask_b32_e64 v208, v245, v4, s[6:7]
	v_add_f32_e32 v4, v61, v65
	v_cndmask_b32_e64 v203, v245, v4, s[96:97]
	v_add_f32_e32 v4, v60, v64
	v_cndmask_b32_e64 v209, v245, v4, s[92:93]
	v_add_f32_e32 v4, v59, v15
	v_cndmask_b32_e64 v210, v245, v4, s[88:89]
	v_add_f32_e32 v4, v58, v13
	v_cndmask_b32_e64 v211, v245, v4, s[84:85]
	v_add_f32_e32 v4, v57, v12
	v_cndmask_b32_e64 v206, v245, v4, s[80:81]
	v_add_f32_e32 v4, v56, v11
	v_cndmask_b32_e64 v207, v245, v4, s[76:77]
	v_add_f32_e32 v4, v55, v10
	v_cndmask_b32_e64 v212, v245, v4, s[72:73]
	v_add_f32_e32 v4, v54, v9
	v_cndmask_b32_e64 v213, v245, v4, s[68:69]
	v_add_f32_e32 v4, v53, v8
	v_cndmask_b32_e64 v70, v245, v4, s[64:65]
	v_add_f32_e32 v4, v52, v7
	v_cndmask_b32_e64 v71, v245, v4, s[60:61]
	v_add_f32_e32 v4, v51, v6
	v_cndmask_b32_e64 v68, v245, v4, s[56:57]
	v_add_f32_e32 v4, v50, v5
	v_add_f32_e32 v2, v48, v2
	v_cndmask_b32_e64 v69, v245, v4, s[52:53]
	v_add_f32_e32 v3, v49, v3
	v_cndmask_b32_e64 v76, v245, v2, s[20:21]
	s_waitcnt lgkmcnt(0)
; DI unsigned cvtpk(float lo, float hi) { f32x2 v = {lo, hi}; bf16x2_t b = __builtin_convertvector(v, bf16x2_t); return __builtin_bit_cast(unsigned, b); }
; DI float fexp2(float x) { return __builtin_amdgcn_exp2f(x); }
; DI float max2f(float a, float b) { float r; asm("v_max_f32_e32 %0, %1, %2" : "=v"(r) : "v"(a), "v"(b)); return r; }
; DI float xhalf_max(float v) { auto rr = __builtin_amdgcn_permlane32_swap(__float_as_uint(v), __float_as_uint(v), false, false); return max2f(__uint_as_float(rr[0]), __uint_as_float(rr[1])); }
; DI void softmax_pv(f32x16& p0, f32x16& p1, float& m, float& l, f32x16& o0, f32x16& o1, LAS const unsigned char* vslot, int lane, int hi) {
;     ...
;     for (int ks = 0; ks < 4; ++ks) { vlo0[ks] = vtr(vp + ks * 1024); vhi0[ks] = vtr(vp + ks * 1024 + 512); vlo1[ks] = vtr(vp + 4096 + ks * 1024); vhi1[ks] = vtr(vp + 4096 + ks * 1024 + 512); }
;     __builtin_amdgcn_sched_barrier(0);
;     const float mx = xhalf_max(rowmax32(p0, p1));
;     const float mn = max2f(m, mx); const float f = fexp2(m - mn); m = mn;
;     float s = 0.f;
; #pragma unroll
;     for (int r = 0; r < 16; ++r) { p0[r] = fexp2(p0[r] - mn); p1[r] = fexp2(p1[r] - mn); s += p0[r] + p1[r]; }
;     s = xhalf_sum(s);
;     l = l * f + s;
; #pragma unroll
;     for (int r = 0; r < 16; ++r) { o0[r] *= f; o1[r] *= f; }
;     u32x4 pw[4];
;     pw[0] = (u32x4){cvtpk(p0[0], p0[1]), cvtpk(p0[2], p0[3]), cvtpk(p0[4], p0[5]), cvtpk(p0[6], p0[7])};
;     pw[1] = (u32x4){cvtpk(p0[8], p0[9]), cvtpk(p0[10], p0[11]), cvtpk(p0[12], p0[13]), cvtpk(p0[14], p0[15])};
;     pw[2] = (u32x4){cvtpk(p1[0], p1[1]), cvtpk(p1[2], p1[3]), cvtpk(p1[4], p1[5]), cvtpk(p1[6], p1[7])};
;     pw[3] = (u32x4){cvtpk(p1[8], p1[9]), cvtpk(p1[10], p1[11]), cvtpk(p1[12], p1[13]), cvtpk(p1[14], p1[15])};
; #pragma unroll
;     for (int ks = 0; ks < 4; ++ks) {
;         const bf16x8 v0 = (bf16x8){vlo0[ks][0], vlo0[ks][1], vlo0[ks][2], vlo0[ks][3], vhi0[ks][0], vhi0[ks][1], vhi0[ks][2], vhi0[ks][3]};
;         const bf16x8 v1 = (bf16x8){vlo1[ks][0], vlo1[ks][1], vlo1[ks][2], vlo1[ks][3], vhi1[ks][0], vhi1[ks][1], vhi1[ks][2], vhi1[ks][3]};
;         const bf16x8 pf = __builtin_bit_cast(bf16x8, pw[ks]);
;         o0 = __builtin_amdgcn_mfma_f32_32x32x16_bf16(v0, pf, o0, 0, 0, 0);
;         o1 = __builtin_amdgcn_mfma_f32_32x32x16_bf16(v1, pf, o1, 0, 0, 0);
;     }
	v_add_f32_e32 v2, v63, v66
	v_add_u32_e32 v4, v178, v177
	v_cndmask_b32_e64 v15, v245, v3, s[48:49]
	v_cndmask_b32_e64 v214, v245, v2, s[10:11]
	ds_read_b64_tr_b16 v[64:65], v4 offset:24576
	ds_read_b64_tr_b16 v[66:67], v4 offset:25088
	ds_read_b64_tr_b16 v[60:61], v4 offset:28672
	ds_read_b64_tr_b16 v[62:63], v4 offset:29184
	ds_read_b64_tr_b16 v[52:53], v4 offset:25600
	ds_read_b64_tr_b16 v[54:55], v4 offset:26112
	ds_read_b64_tr_b16 v[56:57], v4 offset:29696
	ds_read_b64_tr_b16 v[58:59], v4 offset:30208
	ds_read_b64_tr_b16 v[48:49], v4 offset:26624
	ds_read_b64_tr_b16 v[50:51], v4 offset:27136
	ds_read_b64_tr_b16 v[10:11], v4 offset:30720
	ds_read_b64_tr_b16 v[12:13], v4 offset:31232
	ds_read_b64_tr_b16 v[6:7], v4 offset:27648
	ds_read_b64_tr_b16 v[8:9], v4 offset:28160
	ds_read_b64_tr_b16 v[2:3], v4 offset:31744
	ds_read_b64_tr_b16 v[4:5], v4 offset:32256
	v_max3_f32 v77, v14, v0, v76
	v_max3_f32 v78, v168, v167, v15
	s_nop 0
	v_max3_f32 v77, v77, v69, v68
	v_max3_f32 v78, v78, v198, v197
	s_nop 0
	v_max3_f32 v77, v77, v196, v169
	v_max3_f32 v78, v78, v213, v212
	s_nop 0
	v_max3_f32 v77, v77, v71, v70
	v_max3_f32 v78, v78, v202, v201
	s_nop 0
	v_max3_f32 v77, v77, v200, v199
	v_max3_f32 v78, v78, v211, v210
	s_nop 0
	v_max3_f32 v77, v77, v207, v206
	v_max3_f32 v78, v78, v74, v72
	s_nop 0
	v_max3_f32 v77, v77, v75, v73
	v_max3_f32 v78, v78, v208, v214
	s_nop 0
	v_max3_f32 v77, v77, v209, v203
	s_nop 0
	v_max_f32_e32 v77, v77, v78
	s_nop 0
	v_mov_b32_e32 v78, v77
	s_nop 1
	v_permlane32_swap_b32_e32 v77, v78
	v_max_f32_e32 v77, v77, v78
	s_nop 0
	v_max_f32_e32 v215, v194, v77
	s_nop 0
	v_sub_f32_e32 v14, v14, v215
	v_exp_f32_e32 v216, v14
	v_sub_f32_e32 v14, v76, v215
	v_sub_f32_e32 v0, v0, v215
	v_exp_f32_e32 v217, v14
	v_exp_f32_e32 v76, v0
	v_sub_f32_e32 v0, v15, v215
	v_exp_f32_e32 v0, v0
	v_add_f32_e32 v77, v216, v217
	v_sub_f32_e32 v194, v194, v215
	v_exp_f32_e32 v194, v194
	v_pk_add_f32 v[14:15], v[76:77], v[0:1]
	v_sub_f32_e32 v75, v75, v215
	v_pk_add_f32 v[14:15], v[14:15], v[14:15] op_sel_hi:[0,1]
	v_sub_f32_e32 v14, v168, v215
	v_exp_f32_e32 v77, v14
	v_sub_f32_e32 v14, v69, v215
	v_exp_f32_e32 v218, v14
	v_sub_f32_e32 v14, v167, v215
	v_exp_f32_e32 v78, v14
	v_sub_f32_e32 v14, v68, v215
	v_exp_f32_e32 v14, v14
	v_add_f32_e32 v79, v77, v218
	v_sub_f32_e32 v73, v73, v215
	v_pk_mul_f32 v[30:31], v[30:31], v[194:195] op_sel_hi:[1,0]
	v_pk_add_f32 v[68:69], v[78:79], v[14:15]
	v_sub_f32_e32 v15, v196, v215
	v_pk_add_f32 v[68:69], v[68:69], v[68:69] op_sel_hi:[0,1]
	v_sub_f32_e32 v68, v71, v215
	v_exp_f32_e32 v79, v68
	v_sub_f32_e32 v68, v169, v215
	v_exp_f32_e32 v15, v15
	v_exp_f32_e32 v168, v68
	v_sub_f32_e32 v68, v70, v215
	v_exp_f32_e32 v68, v68
	v_add_f32_e32 v169, v15, v79
	v_pk_mul_f32 v[28:29], v[28:29], v[194:195] op_sel_hi:[1,0]
	v_pk_mul_f32 v[26:27], v[26:27], v[194:195] op_sel_hi:[1,0]
	v_pk_add_f32 v[70:71], v[168:169], v[68:69]
	v_sub_f32_e32 v69, v198, v215
	v_pk_add_f32 v[204:205], v[70:71], v[70:71] op_sel_hi:[0,1]
	v_sub_f32_e32 v70, v213, v215
	v_exp_f32_e32 v167, v70
	v_sub_f32_e32 v70, v197, v215
	v_exp_f32_e32 v69, v69
	v_exp_f32_e32 v196, v70
	v_sub_f32_e32 v70, v212, v215
	v_exp_f32_e32 v204, v70
	v_add_f32_e32 v197, v69, v167
	v_pk_mul_f32 v[24:25], v[24:25], v[194:195] op_sel_hi:[1,0]
	v_pk_mul_f32 v[22:23], v[22:23], v[194:195] op_sel_hi:[1,0]
	v_pk_add_f32 v[70:71], v[196:197], v[204:205]
	v_exp_f32_e32 v205, v75
	v_pk_add_f32 v[70:71], v[70:71], v[70:71] op_sel_hi:[0,1]
	v_sub_f32_e32 v70, v200, v215
	v_exp_f32_e32 v169, v70
	v_sub_f32_e32 v70, v207, v215
	v_exp_f32_e32 v197, v70
	v_sub_f32_e32 v70, v199, v215
	v_exp_f32_e32 v198, v70
	v_sub_f32_e32 v70, v206, v215
	v_exp_f32_e32 v70, v70
	v_add_f32_e32 v199, v169, v197
	v_pk_mul_f32 v[20:21], v[20:21], v[194:195] op_sel_hi:[1,0]
	v_pk_mul_f32 v[18:19], v[18:19], v[194:195] op_sel_hi:[1,0]
	v_pk_add_f32 v[206:207], v[198:199], v[70:71]
	v_sub_f32_e32 v71, v202, v215
	v_exp_f32_e32 v202, v73
	v_sub_f32_e32 v73, v74, v215
	v_pk_mul_f32 v[16:17], v[16:17], v[194:195] op_sel_hi:[1,0]
	v_pk_mul_f32 v[46:47], v[46:47], v[194:195] op_sel_hi:[1,0]
	v_cvt_pk_bf16_f32 v74, v216, v76
	v_cvt_pk_bf16_f32 v75, v77, v78
	v_cvt_pk_bf16_f32 v76, v15, v168
	v_cvt_pk_bf16_f32 v77, v69, v196
	v_pk_mul_f32 v[44:45], v[44:45], v[194:195] op_sel_hi:[1,0]
	v_pk_mul_f32 v[42:43], v[42:43], v[194:195] op_sel_hi:[1,0]
	v_pk_mul_f32 v[40:41], v[40:41], v[194:195] op_sel_hi:[1,0]
	v_pk_mul_f32 v[38:39], v[38:39], v[194:195] op_sel_hi:[1,0]
	v_pk_mul_f32 v[36:37], v[36:37], v[194:195] op_sel_hi:[1,0]
	v_pk_mul_f32 v[34:35], v[34:35], v[194:195] op_sel_hi:[1,0]
	v_pk_mul_f32 v[32:33], v[32:33], v[194:195] op_sel_hi:[1,0]
	s_waitcnt lgkmcnt(14)
	v_mfma_f32_32x32x16_bf16 v[16:31], v[64:67], v[74:77], v[16:31]
	v_sub_f32_e32 v200, v201, v215
	v_sub_f32_e32 v15, v72, v215
	v_exp_f32_e32 v71, v71
	v_exp_f32_e32 v200, v200
	v_exp_f32_e32 v65, v73
	v_exp_f32_e32 v64, v15
	v_sub_f32_e32 v199, v211, v215
	s_waitcnt lgkmcnt(12)
	v_mfma_f32_32x32x16_bf16 v[32:47], v[60:63], v[74:77], v[32:47]
	v_pk_add_f32 v[206:207], v[206:207], v[206:207] op_sel_hi:[0,1]
	v_exp_f32_e32 v66, v199
	v_sub_f32_e32 v15, v210, v215
	v_cvt_pk_bf16_f32 v60, v169, v198
	v_cvt_pk_bf16_f32 v61, v71, v200
	v_cvt_pk_bf16_f32 v62, v205, v202
	v_cvt_pk_bf16_f32 v63, v65, v64
	v_exp_f32_e32 v206, v15
	v_add_f32_e32 v201, v71, v66
	s_waitcnt lgkmcnt(10)
	v_mfma_f32_32x32x16_bf16 v[16:31], v[52:55], v[60:63], v[16:31]
	v_sub_f32_e32 v15, v209, v215
	v_add_f32_e64 v52, v200, v206
	v_add_f32_e64 v53, v201, v207
	v_cvt_pk_bf16_f32 v54, v79, v68
	v_cvt_pk_bf16_f32 v55, v167, v204
	s_waitcnt lgkmcnt(8)
	v_mfma_f32_32x32x16_bf16 v[32:47], v[56:59], v[60:63], v[32:47]
	v_add_f32_e64 v56, v52, v52
	v_add_f32_e64 v57, v52, v53
	v_exp_f32_e32 v58, v15
	v_cvt_pk_bf16_f32 v52, v217, v0
	v_sub_f32_e32 v0, v203, v215
	v_exp_f32_e32 v56, v0
	v_cvt_pk_bf16_f32 v53, v218, v14
	v_add_f32_e32 v203, v205, v58
	v_sub_f32_e32 v0, v208, v215
	s_waitcnt lgkmcnt(6)
	v_mfma_f32_32x32x16_bf16 v[16:31], v[48:51], v[52:55], v[16:31]
	v_add_f32_e64 v14, v202, v56
	v_add_f32_e64 v15, v203, v57
	v_exp_f32_e32 v0, v0
	v_pk_add_f32 v[14:15], v[14:15], v[14:15] op_sel_hi:[0,1]
	v_add_f32_e32 v65, v65, v0
	s_waitcnt lgkmcnt(4)
	v_mfma_f32_32x32x16_bf16 v[32:47], v[10:13], v[52:55], v[32:47]
	v_sub_f32_e32 v10, v214, v215
	v_exp_f32_e32 v14, v10
	v_cvt_pk_bf16_f32 v10, v197, v70
	v_cvt_pk_bf16_f32 v11, v66, v206
	v_cvt_pk_bf16_f32 v12, v58, v56
	v_cvt_pk_bf16_f32 v13, v0, v14
	s_waitcnt lgkmcnt(2)
	s_nop 0
	v_mfma_f32_32x32x16_bf16 v[16:31], v[6:9], v[10:13], v[16:31]
	v_add_f32_e64 v6, v64, v14
	v_add_f32_e64 v7, v65, v15
	v_pk_add_f32 v[6:7], v[6:7], v[6:7] op_sel:[0,1] op_sel_hi:[1,0]
	s_nop 0
	v_mov_b32_e32 v0, v6
	s_nop 1
	v_permlane32_swap_b32_e32 v6, v0
	s_waitcnt lgkmcnt(0)
	v_mfma_f32_32x32x16_bf16 v[32:47], v[2:5], v[10:13], v[32:47]
	v_add_f32_e32 v0, v6, v0
	v_fmac_f32_e32 v0, v193, v194
	v_mov_b32_e32 v194, v215
	v_mov_b32_e32 v193, v0
	s_cmp_lg_u32 s0, 8
	s_cbranch_scc1 .LBB0_416
